# v36 + nt hint on the P10 single-use id and gate loads
# baseline (speedup 1.0000x reference)
; DI void phase10(const Params& p) {
;     ...
;   for (int i = blockIdx.x * 256 + threadIdx.x; i < T_ * 128; i += gridDim.x * 256) {
;     int ai = 0;
; #pragma unroll
;     for (int s = 0; s < 8; ++s) ai += PA[(size_t)s * T_ * 128 + i];
;     const int id = IDS[i];
;     const float a = (float)ai * USC[id] * HSC[i >> 7];
;     ACT[i] = 0.5f * a * (1.f + erff(a * 0.70710678118654752f)) * GATE[i] * VSC[id];
;   }
.LBB0_1189:
	s_or_b64 exec, exec, s[22:23]
	v_lshl_add_u64 v[12:13], s[14:15], 0, v[4:5]
	v_lshl_add_u64 v[6:7], v[6:7], 2, s[18:19]
	global_load_dword v14, v[12:13], off nt
	global_load_dword v15, v[6:7], off
	v_bfi_b32 v6, s35, v11, v10
	v_mul_f32_e32 v3, 0.5, v3
	v_add_f32_e32 v6, 1.0, v6
	v_add_u32_e32 v2, s13, v2
	v_mul_f32_e32 v3, v3, v6
	v_cmp_lt_i32_e32 vcc, s36, v2
	v_lshl_add_u64 v[4:5], s[6:7], 0, v[4:5]
	s_or_b64 s[20:21], vcc, s[20:21]
	s_waitcnt vmcnt(1)
	v_mul_f32_e32 v3, v14, v3
	s_waitcnt vmcnt(0)
	v_mul_f32_e32 v3, v15, v3
	global_store_dword v[4:5], v3, off
	s_andn2_b64 exec, exec, s[20:21]
	s_cbranch_execz .LBB0_1194
.LBB0_1190:
	v_ashrrev_i32_e32 v3, 31, v2
	v_lshlrev_b64 v[4:5], 2, v[2:3]
	v_lshl_add_u64 v[6:7], s[10:11], 0, v[4:5]
	global_load_dword v6, v[6:7], off nt
	v_lshl_add_u64 v[10:11], s[4:5], 0, v[4:5]
	v_add_co_u32_e32 v12, vcc, 0x400000, v10
	s_waitcnt vmcnt(0)
	v_ashrrev_i32_e32 v7, 31, v6
	v_addc_co_u32_e32 v13, vcc, 0, v11, vcc
	v_add_co_u32_e32 v14, vcc, 0x800000, v10
	s_nop 1
	v_addc_co_u32_e32 v15, vcc, 0, v11, vcc
	v_add_co_u32_e32 v16, vcc, 0xc00000, v10
	s_nop 1
	v_addc_co_u32_e32 v17, vcc, 0, v11, vcc
	v_add_co_u32_e32 v18, vcc, 0x1000000, v10
	s_nop 1
	v_addc_co_u32_e32 v19, vcc, 0, v11, vcc
	v_add_co_u32_e32 v20, vcc, 0x1400000, v10
	s_nop 1
	v_addc_co_u32_e32 v21, vcc, 0, v11, vcc
	v_add_co_u32_e32 v22, vcc, 0x1800000, v10
	s_nop 1
	v_addc_co_u32_e32 v23, vcc, 0, v11, vcc
	v_add_co_u32_e32 v24, vcc, 0x1c00000, v10
	s_nop 1
	v_addc_co_u32_e32 v25, vcc, 0, v11, vcc
	global_load_dword v3, v[10:11], off nt
	global_load_dword v26, v[12:13], off nt
	global_load_dword v27, v[14:15], off nt
	global_load_dword v28, v[16:17], off nt
	global_load_dword v29, v[18:19], off nt
	global_load_dword v30, v[20:21], off nt
	global_load_dword v31, v[22:23], off nt
	global_load_dword v32, v[24:25], off nt
	v_ashrrev_i32_e32 v10, 7, v2
	v_ashrrev_i32_e32 v11, 31, v10
	v_lshl_add_u64 v[10:11], v[10:11], 2, s[8:9]
	global_load_dword v12, v[10:11], off
	v_lshl_add_u64 v[10:11], v[6:7], 2, s[16:17]
	global_load_dword v10, v[10:11], off
	s_waitcnt vmcnt(8)
	v_add_u32_e32 v3, v26, v3
	s_waitcnt vmcnt(6)
	v_add3_u32 v3, v3, v27, v28
	s_waitcnt vmcnt(4)
	v_add3_u32 v3, v3, v29, v30
	s_waitcnt vmcnt(2)
	v_add3_u32 v3, v3, v31, v32
	v_cvt_f32_i32_e32 v3, v3
	s_waitcnt vmcnt(0)
	v_mul_f32_e32 v3, v10, v3
	v_mul_f32_e32 v3, v3, v12
	v_mul_f32_e32 v10, 0x3f3504f3, v3
	v_cmp_nlt_f32_e64 s[22:23], |v10|, 1.0
	s_and_saveexec_b64 s[40:41], s[22:23]
	s_xor_b64 s[22:23], exec, s[40:41]
	s_cbranch_execz .LBB0_1192
	v_fma_f32 v11, |v10|, s24, v8
	v_fma_f32 v11, |v10|, v11, s25
	v_fma_f32 v11, |v10|, v11, s26
	v_fma_f32 v11, |v10|, v11, s27
	v_fma_f32 v11, |v10|, v11, s28
	v_fma_f32 v11, |v10|, v11, s29
	v_fma_f32 v11, |v10|, v11, |v10|
	v_mul_f32_e32 v12, 0xbfb8aa3b, v11
	v_fma_f32 v13, v11, s30, -v12
	v_rndne_f32_e32 v14, v12
	v_fmac_f32_e32 v13, 0xb2a5705f, v11
	v_sub_f32_e32 v12, v12, v14
	v_add_f32_e32 v12, v12, v13
	v_cvt_i32_f32_e32 v13, v14
	v_exp_f32_e32 v12, v12
	v_cmp_nlt_f32_e32 vcc, s31, v11
	v_ldexp_f32 v12, v12, v13
	s_nop 0
	v_cndmask_b32_e32 v12, 0, v12, vcc
	v_cmp_ngt_f32_e32 vcc, s34, v11
	s_nop 1
	v_cndmask_b32_e32 v11, v9, v12, vcc
	v_sub_f32_e32 v11, 1.0, v11
